# ssd_p2: both 17-chunk load batches issued up front into renamed registers, chains run back to back
# speedup vs baseline: 1.0056x; 1.0020x over previous
.LBB0_300:
	v_mov_b32_e32 v1, v0
	s_add_i32 s2, s15, s16
	v_readlane_b32 s0, v254, 1
	v_lshl_add_u32 v1, s2, 8, v1
	s_waitcnt vmcnt(0)
	v_bfe_u32 v6, v1, 13, 1
	v_bfe_u32 v5, v1, 14, 4
	v_lshlrev_b32_e32 v2, 14, v6
	v_and_b32_e32 v4, 0x1fff, v1
	v_lshl_or_b32 v130, v5, 15, v2
	v_readlane_b32 s1, v254, 2
	v_ashrrev_i32_e32 v7, 18, v1
	v_and_b32_e32 v1, 0x2000, v1
	v_lshl_add_u64 v[2:3], s[0:1], 0, v[130:131]
	v_lshlrev_b32_e32 v130, 1, v4
	v_readlane_b32 s0, v254, 3
	v_lshl_add_u64 v[2:3], v[2:3], 0, v[130:131]
	v_lshlrev_b32_e32 v130, 7, v5
	v_readlane_b32 s1, v254, 4
	v_cmp_eq_u32_e64 s[2:3], 0, v6
	v_cmp_ne_u32_e64 s[4:5], 0, v1
	v_lshl_add_u64 v[4:5], s[0:1], 0, v[130:131]
	v_lshlrev_b32_e32 v130, 2, v6
	v_lshlrev_b32_e32 v1, 5, v7
	v_lshlrev_b32_e32 v6, 1, v7
	v_lshl_add_u64 v[4:5], v[4:5], 0, v[130:131]
	v_add_u32_e32 v38, 0x81, v6
	v_add_u32_e32 v39, -2, v1
	v_add_u32_e32 v40, 0x80, v6
	v_mov_b32_e32 v41, 0
	s_movk_i32 s20, 0xffef
	s_mov_b32 s17, 0
	s_mov_b32 s18, 0
	s_branch .LBB0_302
.LBB0_302:
	s_add_i32 s19, s20, 17
	s_cmp_gt_u32 s19, 1
	s_cselect_b64 s[6:7], -1, 0
	s_and_saveexec_b64 s[8:9], s[4:5]
	s_xor_b64 s[8:9], exec, s[8:9]
	s_cbranch_execz .LBB0_307
	s_mov_b64 s[10:11], -1
	s_and_b64 vcc, exec, s[6:7]
	s_cbranch_vccz .LBB0_305
	v_add3_u32 v6, v1, s17, 33
	s_mov_b64 s[10:11], 0

.Lp2_mid:
	s_or_b64 exec, exec, s[8:9]
	s_add_i32 s18, s18, 17
	s_sub_i32 s17, s17, 17
	s_mov_b32 s20, s19
.Lp2b_302:
	s_add_i32 s19, s20, 17
	s_cmp_gt_u32 s19, 1
	s_cselect_b64 s[6:7], -1, 0
	s_and_saveexec_b64 s[8:9], s[4:5]
	s_xor_b64 s[8:9], exec, s[8:9]
	s_cbranch_execz .Lp2b_307
	s_mov_b64 s[10:11], -1
	s_and_b64 vcc, exec, s[6:7]
	s_cbranch_vccz .Lp2b_305
	v_add3_u32 v218, v1, s17, 33
	s_mov_b64 s[10:11], 0
.Lp2b_305:
	s_andn2_b64 vcc, exec, s[10:11]
	s_cbranch_vccnz .Lp2b_307
	v_subrev_u32_e32 v218, s18, v38
.Lp2b_307:
	s_andn2_saveexec_b64 s[8:9], s[8:9]
	s_cbranch_execz .Lp2b_312
	s_mov_b64 s[10:11], -1
	s_and_b64 vcc, exec, s[6:7]
	s_cbranch_vccz .Lp2b_310
	v_add_u32_e32 v218, s18, v39
	s_mov_b64 s[10:11], 0
.Lp2b_310:
	s_andn2_b64 vcc, exec, s[10:11]
	s_cbranch_vccnz .Lp2b_312
	v_or_b32_e32 v218, s18, v40
.Lp2b_312:
	s_or_b64 exec, exec, s[8:9]
	v_lshlrev_b32_e32 v130, 18, v218
	v_lshlrev_b32_e32 v218, 9, v218
	v_ashrrev_i32_e32 v219, 31, v218
	v_lshl_add_u64 v[220:221], v[130:131], 1, v[2:3]
	v_lshl_add_u64 v[218:219], v[218:219], 2, v[4:5]
	s_cmpk_eq_i32 s20, 0xffef
	v_add_u32_e32 v114, s17, v1
	v_add_u32_e32 v144, s20, v1
	global_load_ushort v105, v[220:221], off
	global_load_dword v104, v[218:219], off
	s_cselect_b64 vcc, -1, 0
	v_add_u32_e32 v218, 32, v114
	v_add_u32_e32 v219, 16, v144
	v_cndmask_b32_e32 v218, v218, v40, vcc
	v_cndmask_b32_e32 v219, v219, v38, vcc
	v_cndmask_b32_e64 v220, v218, v219, s[2:3]
	v_lshlrev_b32_e32 v130, 18, v220
	v_lshlrev_b32_e32 v220, 9, v220
	v_ashrrev_i32_e32 v221, 31, v220
	v_lshl_add_u64 v[218:219], v[130:131], 1, v[2:3]
	v_lshl_add_u64 v[220:221], v[220:221], 2, v[4:5]
	global_load_ushort v108, v[218:219], off
	global_load_dword v106, v[220:221], off
	v_add_u32_e32 v220, 17, v144
	v_add_u32_e32 v221, 31, v114
	v_cndmask_b32_e64 v222, v221, v220, s[2:3]
	v_lshlrev_b32_e32 v130, 18, v222
	v_lshlrev_b32_e32 v222, 9, v222
	v_ashrrev_i32_e32 v223, 31, v222
	v_lshl_add_u64 v[220:221], v[130:131], 1, v[2:3]
	v_lshl_add_u64 v[222:223], v[222:223], 2, v[4:5]
	global_load_ushort v110, v[220:221], off
	global_load_dword v107, v[222:223], off
	v_add_u32_e32 v222, 18, v144
	v_add_u32_e32 v223, 30, v114
	v_cndmask_b32_e64 v224, v223, v222, s[2:3]
	v_lshlrev_b32_e32 v130, 18, v224
	v_lshlrev_b32_e32 v224, 9, v224
	v_ashrrev_i32_e32 v225, 31, v224
	v_lshl_add_u64 v[222:223], v[130:131], 1, v[2:3]
	v_lshl_add_u64 v[224:225], v[224:225], 2, v[4:5]
	global_load_ushort v112, v[222:223], off
	global_load_dword v109, v[224:225], off
	v_add_u32_e32 v224, 19, v144
	v_add_u32_e32 v225, 29, v114
	v_cndmask_b32_e64 v226, v225, v224, s[2:3]
	v_lshlrev_b32_e32 v130, 18, v226
	v_lshlrev_b32_e32 v226, 9, v226
	v_ashrrev_i32_e32 v227, 31, v226
	v_lshl_add_u64 v[224:225], v[130:131], 1, v[2:3]
	v_lshl_add_u64 v[226:227], v[226:227], 2, v[4:5]
	global_load_ushort v115, v[224:225], off
	global_load_dword v111, v[226:227], off
	v_add_u32_e32 v226, 20, v144
	v_add_u32_e32 v227, 28, v114
	v_cndmask_b32_e64 v228, v227, v226, s[2:3]
	v_lshlrev_b32_e32 v130, 18, v228
	v_lshlrev_b32_e32 v228, 9, v228
	v_ashrrev_i32_e32 v229, 31, v228
	v_lshl_add_u64 v[226:227], v[130:131], 1, v[2:3]
	v_lshl_add_u64 v[228:229], v[228:229], 2, v[4:5]
	global_load_ushort v116, v[226:227], off
	global_load_dword v113, v[228:229], off
	v_add_u32_e32 v228, 21, v144
	v_add_u32_e32 v229, 27, v114
	v_cndmask_b32_e64 v230, v229, v228, s[2:3]
	v_lshlrev_b32_e32 v130, 18, v230
	v_lshlrev_b32_e32 v230, 9, v230
	v_ashrrev_i32_e32 v231, 31, v230
	v_lshl_add_u64 v[228:229], v[130:131], 1, v[2:3]
	v_lshl_add_u64 v[230:231], v[230:231], 2, v[4:5]
	global_load_ushort v118, v[228:229], off
	global_load_dword v117, v[230:231], off
	v_add_u32_e32 v230, 22, v144
	v_add_u32_e32 v231, 26, v114
	v_cndmask_b32_e64 v232, v231, v230, s[2:3]
	v_lshlrev_b32_e32 v130, 18, v232
	v_lshlrev_b32_e32 v232, 9, v232
	v_ashrrev_i32_e32 v233, 31, v232
	v_lshl_add_u64 v[230:231], v[130:131], 1, v[2:3]
	v_lshl_add_u64 v[232:233], v[232:233], 2, v[4:5]
	global_load_ushort v121, v[230:231], off
	global_load_dword v119, v[232:233], off
	v_add_u32_e32 v232, 23, v144
	v_add_u32_e32 v233, 25, v114
	v_cndmask_b32_e64 v234, v233, v232, s[2:3]
	v_lshlrev_b32_e32 v130, 18, v234
	v_lshlrev_b32_e32 v234, 9, v234
	v_ashrrev_i32_e32 v235, 31, v234
	v_lshl_add_u64 v[232:233], v[130:131], 1, v[2:3]
	v_lshl_add_u64 v[234:235], v[234:235], 2, v[4:5]
	global_load_ushort v124, v[232:233], off
	global_load_dword v120, v[234:235], off
	v_add_u32_e32 v234, 24, v144
	v_add_u32_e32 v235, 24, v114
	v_cndmask_b32_e64 v236, v235, v234, s[2:3]
	v_lshlrev_b32_e32 v130, 18, v236
	v_lshlrev_b32_e32 v236, 9, v236
	v_ashrrev_i32_e32 v237, 31, v236
	v_lshl_add_u64 v[234:235], v[130:131], 1, v[2:3]
	v_lshl_add_u64 v[236:237], v[236:237], 2, v[4:5]
	global_load_ushort v126, v[234:235], off
	global_load_dword v122, v[236:237], off
	v_add_u32_e32 v236, 25, v144
	v_add_u32_e32 v237, 23, v114
	v_cndmask_b32_e64 v238, v237, v236, s[2:3]
	v_lshlrev_b32_e32 v130, 18, v238
	v_lshlrev_b32_e32 v238, 9, v238
	v_ashrrev_i32_e32 v239, 31, v238
	v_lshl_add_u64 v[236:237], v[130:131], 1, v[2:3]
	v_lshl_add_u64 v[238:239], v[238:239], 2, v[4:5]
	global_load_ushort v128, v[236:237], off
	global_load_dword v123, v[238:239], off
	v_add_u32_e32 v238, 26, v144
	v_add_u32_e32 v239, 22, v114
	v_cndmask_b32_e64 v240, v239, v238, s[2:3]
	v_lshlrev_b32_e32 v130, 18, v240
	v_lshlrev_b32_e32 v240, 9, v240
	v_ashrrev_i32_e32 v241, 31, v240
	v_lshl_add_u64 v[238:239], v[130:131], 1, v[2:3]
	v_lshl_add_u64 v[240:241], v[240:241], 2, v[4:5]
	global_load_ushort v138, v[238:239], off
	global_load_dword v125, v[240:241], off
	v_add_u32_e32 v240, 27, v144
	v_add_u32_e32 v241, 21, v114
	v_cndmask_b32_e64 v242, v241, v240, s[2:3]
	v_lshlrev_b32_e32 v130, 18, v242
	v_lshlrev_b32_e32 v242, 9, v242
	v_ashrrev_i32_e32 v243, 31, v242
	v_lshl_add_u64 v[240:241], v[130:131], 1, v[2:3]
	v_lshl_add_u64 v[242:243], v[242:243], 2, v[4:5]
	global_load_ushort v139, v[240:241], off
	global_load_dword v127, v[242:243], off
	v_add_u32_e32 v242, 28, v144
	v_add_u32_e32 v243, 20, v114
	v_cndmask_b32_e64 v244, v243, v242, s[2:3]
	v_lshlrev_b32_e32 v130, 18, v244
	v_lshlrev_b32_e32 v244, 9, v244
	v_ashrrev_i32_e32 v245, 31, v244
	v_lshl_add_u64 v[242:243], v[130:131], 1, v[2:3]
	v_lshl_add_u64 v[244:245], v[244:245], 2, v[4:5]
	global_load_ushort v142, v[242:243], off
	global_load_dword v129, v[244:245], off
	v_add_u32_e32 v244, 29, v144
	v_add_u32_e32 v245, 19, v114
	v_cndmask_b32_e64 v246, v245, v244, s[2:3]
	v_lshlrev_b32_e32 v130, 18, v246
	v_lshlrev_b32_e32 v246, 9, v246
	v_ashrrev_i32_e32 v247, 31, v246
	v_lshl_add_u64 v[244:245], v[130:131], 1, v[2:3]
	v_lshl_add_u64 v[246:247], v[246:247], 2, v[4:5]
	global_load_ushort v143, v[244:245], off
	global_load_dword v140, v[246:247], off
	v_add_u32_e32 v246, 30, v144
	v_add_u32_e32 v247, 18, v114
	v_cndmask_b32_e64 v248, v247, v246, s[2:3]
	v_lshlrev_b32_e32 v130, 18, v248
	v_lshlrev_b32_e32 v248, 9, v248
	v_ashrrev_i32_e32 v249, 31, v248
	v_lshl_add_u64 v[246:247], v[130:131], 1, v[2:3]
	v_lshl_add_u64 v[248:249], v[248:249], 2, v[4:5]
	global_load_ushort v145, v[246:247], off
	global_load_dword v141, v[248:249], off
	v_add_u32_e32 v248, 31, v144
	v_add_u32_e32 v249, 17, v114
	v_cndmask_b32_e64 v144, v249, v248, s[2:3]
	v_lshlrev_b32_e32 v148, 9, v144
	v_lshlrev_b32_e32 v130, 18, v144
	v_ashrrev_i32_e32 v149, 31, v148
	v_lshl_add_u64 v[248:249], v[130:131], 1, v[2:3]
	v_lshl_add_u64 v[148:149], v[148:149], 2, v[4:5]
	global_load_ushort v146, v[248:249], off
	global_load_dword v144, v[148:149], off
	s_and_saveexec_b64 s[8:9], s[4:5]
	s_xor_b64 s[8:9], exec, s[8:9]
	s_cbranch_execz .Lp2b_317
	s_mov_b64 s[10:11], -1
	s_and_b64 vcc, exec, s[6:7]
	s_cbranch_vccz .Lp2b_315
	v_add_u32_e32 v147, 33, v114
	s_mov_b64 s[10:11], 0
.Lp2b_315:
	s_andn2_b64 vcc, exec, s[10:11]
	s_cbranch_vccnz .Lp2b_317
	v_subrev_u32_e32 v147, s18, v38
.Lp2b_317:
	s_andn2_saveexec_b64 s[8:9], s[8:9]
	s_cbranch_execz .Lp2_chain
	s_mov_b64 s[10:11], -1
	s_and_b64 vcc, exec, s[6:7]
	s_cbranch_vccz .Lp2b_320
	v_add_u32_e32 v147, s18, v39
	s_mov_b64 s[10:11], 0
.Lp2b_320:
	s_andn2_b64 vcc, exec, s[10:11]
	s_cbranch_vccnz .Lp2_chain
	v_or_b32_e32 v147, s18, v40
	s_branch .Lp2_chain
.Lp2_chain:
	s_or_b64 exec, exec, s[8:9]
	s_waitcnt vmcnt(63)
	v_lshlrev_b32_e32 v43, 16, v43
	s_waitcnt vmcnt(63)
	v_lshlrev_b32_e32 v46, 16, v46
	v_fmac_f32_e32 v43, v41, v42
	s_waitcnt vmcnt(63)
	v_lshlrev_b32_e32 v48, 16, v48
	v_lshlrev_b32_e32 v130, 18, v77
	v_fmac_f32_e32 v46, v44, v43
	s_waitcnt vmcnt(61)
	v_lshlrev_b32_e32 v50, 16, v50
	s_waitcnt vmcnt(59)
	v_lshlrev_b32_e32 v78, 16, v53
	v_cvt_pk_bf16_f32 v79, v41, s0
	v_lshl_add_u64 v[52:53], v[130:131], 1, v[2:3]
	v_cvt_pk_bf16_f32 v41, v43, s0
	v_fmac_f32_e32 v48, v45, v46
	global_store_short v[52:53], v79, off
	global_store_short v[6:7], v41, off
	v_cvt_pk_bf16_f32 v6, v46, s0
	v_fmac_f32_e32 v50, v47, v48
	s_waitcnt vmcnt(59)
	v_lshlrev_b32_e32 v54, 16, v54
	global_store_short v[8:9], v6, off
	v_cvt_pk_bf16_f32 v6, v48, s0
	v_fmac_f32_e32 v78, v49, v50
	s_waitcnt vmcnt(58)
	v_lshlrev_b32_e32 v56, 16, v56
	global_store_short v[10:11], v6, off
	v_cvt_pk_bf16_f32 v6, v50, s0
	v_fmac_f32_e32 v54, v51, v78
	s_waitcnt vmcnt(57)
	v_lshlrev_b32_e32 v59, 16, v59
	global_store_short v[12:13], v6, off
	v_cvt_pk_bf16_f32 v6, v78, s0
	v_fmac_f32_e32 v56, v55, v54
	s_waitcnt vmcnt(56)
	v_lshlrev_b32_e32 v62, 16, v62
	global_store_short v[14:15], v6, off
	v_cvt_pk_bf16_f32 v6, v54, s0
	v_fmac_f32_e32 v59, v57, v56
	s_waitcnt vmcnt(55)
	v_lshlrev_b32_e32 v64, 16, v64
	global_store_short v[16:17], v6, off
	v_cvt_pk_bf16_f32 v6, v56, s0
	v_fmac_f32_e32 v62, v58, v59
	s_waitcnt vmcnt(54)
	v_lshlrev_b32_e32 v66, 16, v66
	global_store_short v[18:19], v6, off
	v_cvt_pk_bf16_f32 v6, v59, s0
	v_fmac_f32_e32 v64, v60, v62
	s_waitcnt vmcnt(53)
	v_lshlrev_b32_e32 v68, 16, v68
	global_store_short v[20:21], v6, off
	v_cvt_pk_bf16_f32 v6, v62, s0
	v_fmac_f32_e32 v66, v61, v64
	s_waitcnt vmcnt(52)
	v_lshlrev_b32_e32 v69, 16, v69
	global_store_short v[22:23], v6, off
	v_cvt_pk_bf16_f32 v6, v64, s0
	v_fmac_f32_e32 v68, v63, v66
	s_waitcnt vmcnt(51)
	v_lshlrev_b32_e32 v72, 16, v72
	global_store_short v[24:25], v6, off
	v_cvt_pk_bf16_f32 v6, v66, s0
	v_fmac_f32_e32 v69, v65, v68
	s_waitcnt vmcnt(50)
	v_lshlrev_b32_e32 v73, 16, v73
	global_store_short v[26:27], v6, off
	v_cvt_pk_bf16_f32 v6, v68, s0
	v_fmac_f32_e32 v72, v67, v69
	s_waitcnt vmcnt(49)
	v_lshlrev_b32_e32 v75, 16, v75
	global_store_short v[28:29], v6, off
	v_cvt_pk_bf16_f32 v6, v69, s0
	v_fmac_f32_e32 v73, v70, v72
	s_waitcnt vmcnt(48)
	v_lshlrev_b32_e32 v76, 16, v76
	global_store_short v[30:31], v6, off
	v_cvt_pk_bf16_f32 v6, v72, s0
	v_fmac_f32_e32 v75, v71, v73
	global_store_short v[32:33], v6, off
	v_cvt_pk_bf16_f32 v6, v73, s0
	s_waitcnt vmcnt(49)
	v_fmac_f32_e32 v76, v74, v75
	global_store_short v[34:35], v6, off
	v_cvt_pk_bf16_f32 v6, v75, s0
	v_mov_b32_e32 v41, v76
	global_store_short v[36:37], v6, off
	s_waitcnt vmcnt(50)
	v_lshlrev_b32_e32 v105, 16, v105
	s_waitcnt vmcnt(48)
	v_lshlrev_b32_e32 v108, 16, v108
	v_fmac_f32_e32 v105, v41, v104
	s_waitcnt vmcnt(46)
	v_lshlrev_b32_e32 v110, 16, v110
	v_lshlrev_b32_e32 v130, 18, v147
	v_fmac_f32_e32 v108, v106, v105
	s_waitcnt vmcnt(44)
	v_lshlrev_b32_e32 v112, 16, v112
	s_waitcnt vmcnt(42)
	v_lshlrev_b32_e32 v148, 16, v115
	v_cvt_pk_bf16_f32 v149, v41, s0
	v_lshl_add_u64 v[114:115], v[130:131], 1, v[2:3]
	v_cvt_pk_bf16_f32 v41, v105, s0
	v_fmac_f32_e32 v110, v107, v108
	global_store_short v[114:115], v149, off
	global_store_short v[218:219], v41, off
	v_cvt_pk_bf16_f32 v218, v108, s0
	v_fmac_f32_e32 v112, v109, v110
	s_waitcnt vmcnt(42)
	v_lshlrev_b32_e32 v116, 16, v116
	global_store_short v[220:221], v218, off
	v_cvt_pk_bf16_f32 v218, v110, s0
	v_fmac_f32_e32 v148, v111, v112
	s_waitcnt vmcnt(41)
	v_lshlrev_b32_e32 v118, 16, v118
	global_store_short v[222:223], v218, off
	v_cvt_pk_bf16_f32 v218, v112, s0
	v_fmac_f32_e32 v116, v113, v148
	s_waitcnt vmcnt(40)
	v_lshlrev_b32_e32 v121, 16, v121
	global_store_short v[224:225], v218, off
	v_cvt_pk_bf16_f32 v218, v148, s0
	v_fmac_f32_e32 v118, v117, v116
	s_waitcnt vmcnt(39)
	v_lshlrev_b32_e32 v124, 16, v124
	global_store_short v[226:227], v218, off
	v_cvt_pk_bf16_f32 v218, v116, s0
	v_fmac_f32_e32 v121, v119, v118
	s_waitcnt vmcnt(38)
	v_lshlrev_b32_e32 v126, 16, v126
	global_store_short v[228:229], v218, off
	v_cvt_pk_bf16_f32 v218, v118, s0
	v_fmac_f32_e32 v124, v120, v121
	s_waitcnt vmcnt(37)
	v_lshlrev_b32_e32 v128, 16, v128
	global_store_short v[230:231], v218, off
	v_cvt_pk_bf16_f32 v218, v121, s0
	v_fmac_f32_e32 v126, v122, v124
	s_waitcnt vmcnt(36)
	v_lshlrev_b32_e32 v138, 16, v138
	global_store_short v[232:233], v218, off
	v_cvt_pk_bf16_f32 v218, v124, s0
	v_fmac_f32_e32 v128, v123, v126
	s_waitcnt vmcnt(35)
	v_lshlrev_b32_e32 v139, 16, v139
	global_store_short v[234:235], v218, off
	v_cvt_pk_bf16_f32 v218, v126, s0
	v_fmac_f32_e32 v138, v125, v128
	s_waitcnt vmcnt(34)
	v_lshlrev_b32_e32 v142, 16, v142
	global_store_short v[236:237], v218, off
	v_cvt_pk_bf16_f32 v218, v128, s0
	v_fmac_f32_e32 v139, v127, v138
	s_waitcnt vmcnt(33)
	v_lshlrev_b32_e32 v143, 16, v143
	global_store_short v[238:239], v218, off
	v_cvt_pk_bf16_f32 v218, v138, s0
	v_fmac_f32_e32 v142, v129, v139
	s_waitcnt vmcnt(32)
	v_lshlrev_b32_e32 v145, 16, v145
	global_store_short v[240:241], v218, off
	v_cvt_pk_bf16_f32 v218, v139, s0
	v_fmac_f32_e32 v143, v140, v142
	s_waitcnt vmcnt(31)
	v_lshlrev_b32_e32 v146, 16, v146
	global_store_short v[242:243], v218, off
	v_cvt_pk_bf16_f32 v218, v142, s0
	v_fmac_f32_e32 v145, v141, v143
	global_store_short v[244:245], v218, off
	v_cvt_pk_bf16_f32 v218, v143, s0
	s_waitcnt vmcnt(32)
	v_fmac_f32_e32 v146, v144, v145
	global_store_short v[246:247], v218, off
	v_cvt_pk_bf16_f32 v218, v145, s0
	v_mov_b32_e32 v41, v146
	global_store_short v[248:249], v218, off
	s_branch .LBB0_299
